# scan loop: 47 hazard s_nops per 32 steps replaced by the step's own LDS reads moved into the DPP gaps (waitcnt counts re-derived); scan loop placed +40 bytes
# speedup vs baseline: 1.0037x; 1.0009x over previous
; DEVI float allreduce16(float v) {
;   v = dpp_add<0xB1>(v);
;   v = dpp_add<0x4E>(v);
;   v = dpp_add<0x141>(v);
;   v = dpp_add<0x140>(v);
;   return v;
; }
.LBB0_199:
	ds_read_b128 v[12:15], v96
	ds_read_b128 v[16:19], v96 offset:256
	ds_read_b128 v[20:23], v96 offset:512
	ds_read_b128 v[24:27], v96 offset:768
	ds_read_b128 v[28:31], v96 offset:1024
	ds_read_b32 v102, v91 offset:1280
	ds_read_b128 v[32:35], v96 offset:1344
	ds_read_b128 v[36:39], v96 offset:1600
	ds_read_b128 v[40:43], v96 offset:1856
	ds_read_b128 v[44:47], v96 offset:2112
	ds_read_b128 v[48:51], v96 offset:2368
	ds_read_b32 v104, v91 offset:2624
	s_waitcnt lgkmcnt(8)
	v_pk_mul_f32 v[16:17], v[8:9], v[16:17]
	s_nop 0
	v_pk_fma_f32 v[16:17], v[10:11], v[18:19], v[16:17]
	s_waitcnt lgkmcnt(6)
	v_pk_mul_f32 v[18:19], v[26:27], v[102:103] op_sel_hi:[1,0]
	v_add_f32_e32 v111, v16, v17
	v_pk_mul_f32 v[16:17], v[24:25], v[102:103] op_sel_hi:[1,0]
	v_pk_fma_f32 v[10:11], v[10:11], v[14:15], v[18:19]
	v_pk_fma_f32 v[8:9], v[8:9], v[12:13], v[16:17]
	v_add_f32_dpp v12, v111, v111 quad_perm:[1,0,3,2] row_mask:0xf bank_mask:0xf bound_ctrl:1
	ds_read_b128 v[52:55], v96 offset:2688
	ds_read_b128 v[56:59], v96 offset:2944
	v_add_f32_dpp v12, v12, v12 quad_perm:[2,3,0,1] row_mask:0xf bank_mask:0xf bound_ctrl:1
	ds_read_b128 v[60:63], v96 offset:3200
	ds_read_b128 v[64:67], v96 offset:3456
	v_add_f32_dpp v12, v12, v12 row_half_mirror row_mask:0xf bank_mask:0xf bound_ctrl:1
	ds_read_b128 v[106:109], v96 offset:3712
	ds_read_b32 v110, v91 offset:3968
	v_add_f32_dpp v12, v12, v12 row_mirror row_mask:0xf bank_mask:0xf bound_ctrl:1
	v_pk_fma_f32 v[8:9], v[20:21], v[12:13], v[8:9] op_sel_hi:[1,0,1]
	v_pk_fma_f32 v[10:11], v[22:23], v[12:13], v[10:11] op_sel_hi:[1,0,1]
	v_pk_mul_f32 v[12:13], v[28:29], v[8:9]
	s_nop 0
	v_pk_fma_f32 v[12:13], v[30:31], v[10:11], v[12:13]
	v_add_f32_e32 v113, v12, v13
	s_waitcnt lgkmcnt(8)
	v_pk_mul_f32 v[12:13], v[36:37], v[8:9]
	v_pk_mul_f32 v[8:9], v[32:33], v[8:9]
	v_pk_fma_f32 v[12:13], v[38:39], v[10:11], v[12:13]
	s_waitcnt lgkmcnt(6)
	v_pk_fma_f32 v[8:9], v[44:45], v[104:105], v[8:9] op_sel_hi:[1,0,1]
	v_add_f32_e32 v12, v12, v13
	v_pk_mul_f32 v[10:11], v[34:35], v[10:11]
	ds_read_b128 v[28:31], v96 offset:4032
	v_add_f32_dpp v12, v12, v12 quad_perm:[1,0,3,2] row_mask:0xf bank_mask:0xf bound_ctrl:1
	v_pk_fma_f32 v[10:11], v[46:47], v[104:105], v[10:11] op_sel_hi:[1,0,1]
	ds_read_b128 v[116:119], v96 offset:4288
	v_add_f32_dpp v12, v12, v12 quad_perm:[2,3,0,1] row_mask:0xf bank_mask:0xf bound_ctrl:1
	ds_read_b128 v[120:123], v96 offset:4544
	ds_read_b128 v[124:127], v96 offset:4800
	v_add_f32_dpp v12, v12, v12 row_half_mirror row_mask:0xf bank_mask:0xf bound_ctrl:1
	ds_read_b128 v[128:131], v96 offset:5056
	ds_read_b32 v148, v91 offset:5312
	v_add_f32_dpp v12, v12, v12 row_mirror row_mask:0xf bank_mask:0xf bound_ctrl:1
	v_pk_fma_f32 v[8:9], v[40:41], v[12:13], v[8:9] op_sel_hi:[1,0,1]
	v_pk_fma_f32 v[10:11], v[42:43], v[12:13], v[10:11] op_sel_hi:[1,0,1]
	v_pk_mul_f32 v[12:13], v[48:49], v[8:9]
	s_nop 0
	v_pk_fma_f32 v[12:13], v[50:51], v[10:11], v[12:13]
	v_add_f32_e32 v114, v12, v13
	s_waitcnt lgkmcnt(8)
	v_pk_mul_f32 v[12:13], v[56:57], v[8:9]
	v_pk_mul_f32 v[8:9], v[52:53], v[8:9]
	v_pk_fma_f32 v[12:13], v[58:59], v[10:11], v[12:13]
	s_waitcnt lgkmcnt(6)
	v_pk_fma_f32 v[8:9], v[64:65], v[110:111], v[8:9] op_sel_hi:[1,0,1]
	v_add_f32_e32 v12, v12, v13
	v_pk_mul_f32 v[10:11], v[54:55], v[10:11]
	ds_read_b128 v[48:51], v96 offset:5376
	v_add_f32_dpp v12, v12, v12 quad_perm:[1,0,3,2] row_mask:0xf bank_mask:0xf bound_ctrl:1
	v_pk_fma_f32 v[10:11], v[66:67], v[110:111], v[10:11] op_sel_hi:[1,0,1]
	ds_read_b128 v[132:135], v96 offset:5632
	v_add_f32_dpp v12, v12, v12 quad_perm:[2,3,0,1] row_mask:0xf bank_mask:0xf bound_ctrl:1
	ds_read_b128 v[136:139], v96 offset:5888
	ds_read_b128 v[140:143], v96 offset:6144
	v_add_f32_dpp v12, v12, v12 row_half_mirror row_mask:0xf bank_mask:0xf bound_ctrl:1
	ds_read_b128 v[144:147], v96 offset:6400
	ds_read_b32 v150, v91 offset:6656
	v_add_f32_dpp v12, v12, v12 row_mirror row_mask:0xf bank_mask:0xf bound_ctrl:1
	v_pk_fma_f32 v[32:33], v[60:61], v[12:13], v[8:9] op_sel_hi:[1,0,1]
	v_pk_fma_f32 v[34:35], v[62:63], v[12:13], v[10:11] op_sel_hi:[1,0,1]
	s_waitcnt lgkmcnt(10)
	v_pk_mul_f32 v[36:37], v[116:117], v[32:33]
	v_pk_mul_f32 v[8:9], v[106:107], v[32:33]
	v_pk_fma_f32 v[36:37], v[118:119], v[34:35], v[36:37]
	v_pk_mul_f32 v[28:29], v[28:29], v[32:33]
	v_add_f32_e32 v36, v36, v37
	s_waitcnt lgkmcnt(6)
	v_pk_fma_f32 v[28:29], v[124:125], v[148:149], v[28:29] op_sel_hi:[1,0,1]
	v_pk_mul_f32 v[30:31], v[30:31], v[34:35]
	v_add_f32_dpp v32, v36, v36 quad_perm:[1,0,3,2] row_mask:0xf bank_mask:0xf bound_ctrl:1
	v_pk_fma_f32 v[30:31], v[126:127], v[148:149], v[30:31] op_sel_hi:[1,0,1]
	v_pk_fma_f32 v[8:9], v[108:109], v[34:35], v[8:9]
	v_add_f32_dpp v32, v32, v32 quad_perm:[2,3,0,1] row_mask:0xf bank_mask:0xf bound_ctrl:1
	v_add_f32_e32 v115, v8, v9
	ds_read_b128 v[16:19], v96 offset:6720
	ds_read_b128 v[24:27], v96 offset:6976
	ds_read_b128 v[12:15], v96 offset:7232
	ds_read_b128 v[20:23], v96 offset:7488
	v_add_f32_dpp v32, v32, v32 row_half_mirror row_mask:0xf bank_mask:0xf bound_ctrl:1
	ds_read_b128 v[8:11], v96 offset:7744
	ds_read_b32 v102, v91 offset:8000
	v_add_f32_dpp v32, v32, v32 row_mirror row_mask:0xf bank_mask:0xf bound_ctrl:1
	v_pk_fma_f32 v[52:53], v[120:121], v[32:33], v[28:29] op_sel_hi:[1,0,1]
	v_pk_fma_f32 v[54:55], v[122:123], v[32:33], v[30:31] op_sel_hi:[1,0,1]
	s_waitcnt lgkmcnt(10)
	v_pk_mul_f32 v[56:57], v[132:133], v[52:53]
	v_pk_mul_f32 v[28:29], v[128:129], v[52:53]
	v_pk_fma_f32 v[56:57], v[134:135], v[54:55], v[56:57]
	v_pk_mul_f32 v[48:49], v[48:49], v[52:53]
	v_add_f32_e32 v56, v56, v57
	s_waitcnt lgkmcnt(6)
; DEVI float allreduce16(float v) {
;   v = dpp_add<0xB1>(v);
;   v = dpp_add<0x4E>(v);
;   v = dpp_add<0x141>(v);
;   v = dpp_add<0x140>(v);
;   return v;
; }
	v_pk_fma_f32 v[48:49], v[140:141], v[150:151], v[48:49] op_sel_hi:[1,0,1]
	v_pk_mul_f32 v[50:51], v[50:51], v[54:55]
	v_add_f32_dpp v52, v56, v56 quad_perm:[1,0,3,2] row_mask:0xf bank_mask:0xf bound_ctrl:1
	v_pk_fma_f32 v[50:51], v[142:143], v[150:151], v[50:51] op_sel_hi:[1,0,1]
	v_pk_fma_f32 v[28:29], v[130:131], v[54:55], v[28:29]
	v_add_f32_dpp v52, v52, v52 quad_perm:[2,3,0,1] row_mask:0xf bank_mask:0xf bound_ctrl:1
	v_add_f32_e32 v116, v28, v29
	ds_read_b128 v[36:39], v96 offset:8064
	ds_read_b128 v[44:47], v96 offset:8320
	ds_read_b128 v[32:35], v96 offset:8576
	ds_read_b128 v[40:43], v96 offset:8832
	v_add_f32_dpp v52, v52, v52 row_half_mirror row_mask:0xf bank_mask:0xf bound_ctrl:1
	ds_read_b128 v[28:31], v96 offset:9088
	ds_read_b32 v104, v91 offset:9344
	v_add_f32_dpp v52, v52, v52 row_mirror row_mask:0xf bank_mask:0xf bound_ctrl:1
	v_pk_fma_f32 v[110:111], v[136:137], v[52:53], v[48:49] op_sel_hi:[1,0,1]
	v_pk_fma_f32 v[108:109], v[138:139], v[52:53], v[50:51] op_sel_hi:[1,0,1]
	s_waitcnt lgkmcnt(10)
	v_pk_mul_f32 v[24:25], v[24:25], v[110:111]
	v_pk_mul_f32 v[16:17], v[16:17], v[110:111]
	v_pk_fma_f32 v[24:25], v[26:27], v[108:109], v[24:25]
	s_waitcnt lgkmcnt(6)
	v_pk_fma_f32 v[16:17], v[20:21], v[102:103], v[16:17] op_sel_hi:[1,0,1]
	v_add_f32_e32 v24, v24, v25
	v_pk_mul_f32 v[48:49], v[144:145], v[110:111]
	v_pk_mul_f32 v[18:19], v[18:19], v[108:109]
	v_add_f32_dpp v20, v24, v24 quad_perm:[1,0,3,2] row_mask:0xf bank_mask:0xf bound_ctrl:1
	v_pk_fma_f32 v[48:49], v[146:147], v[108:109], v[48:49]
	v_pk_fma_f32 v[18:19], v[22:23], v[102:103], v[18:19] op_sel_hi:[1,0,1]
	v_add_f32_dpp v20, v20, v20 quad_perm:[2,3,0,1] row_mask:0xf bank_mask:0xf bound_ctrl:1
	v_add_f32_e32 v117, v48, v49
	ds_read_b128 v[56:59], v96 offset:9408
	ds_read_b128 v[64:67], v96 offset:9664
	ds_read_b128 v[52:55], v96 offset:9920
	ds_read_b128 v[60:63], v96 offset:10176
	v_add_f32_dpp v20, v20, v20 row_half_mirror row_mask:0xf bank_mask:0xf bound_ctrl:1
	ds_read_b128 v[48:51], v96 offset:10432
	ds_read_b32 v106, v91 offset:10688
	v_add_f32_dpp v20, v20, v20 row_mirror row_mask:0xf bank_mask:0xf bound_ctrl:1
	v_pk_fma_f32 v[108:109], v[12:13], v[20:21], v[16:17] op_sel_hi:[1,0,1]
	v_pk_fma_f32 v[118:119], v[14:15], v[20:21], v[18:19] op_sel_hi:[1,0,1]
	s_waitcnt lgkmcnt(10)
	v_pk_mul_f32 v[44:45], v[44:45], v[108:109]
	v_pk_mul_f32 v[36:37], v[36:37], v[108:109]
	v_pk_fma_f32 v[44:45], v[46:47], v[118:119], v[44:45]
	s_waitcnt lgkmcnt(6)
	v_pk_fma_f32 v[36:37], v[40:41], v[104:105], v[36:37] op_sel_hi:[1,0,1]
	v_add_f32_e32 v44, v44, v45
	v_pk_mul_f32 v[38:39], v[38:39], v[118:119]
	v_pk_mul_f32 v[8:9], v[8:9], v[108:109]
	v_add_f32_dpp v40, v44, v44 quad_perm:[1,0,3,2] row_mask:0xf bank_mask:0xf bound_ctrl:1
	v_pk_fma_f32 v[38:39], v[42:43], v[104:105], v[38:39] op_sel_hi:[1,0,1]
	v_pk_fma_f32 v[8:9], v[10:11], v[118:119], v[8:9]
	v_add_f32_dpp v40, v40, v40 quad_perm:[2,3,0,1] row_mask:0xf bank_mask:0xf bound_ctrl:1
	v_add_f32_e32 v111, v8, v9
	ds_read_b128 v[8:11], v96 offset:10752
	ds_read_b128 v[12:15], v96 offset:11008
	ds_read_b128 v[16:19], v96 offset:11264
	ds_read_b128 v[20:23], v96 offset:11520
	v_add_f32_dpp v40, v40, v40 row_half_mirror row_mask:0xf bank_mask:0xf bound_ctrl:1
	ds_read_b128 v[24:27], v96 offset:11776
	ds_read_b32 v102, v91 offset:12032
	v_add_f32_dpp v40, v40, v40 row_mirror row_mask:0xf bank_mask:0xf bound_ctrl:1
	v_pk_fma_f32 v[108:109], v[32:33], v[40:41], v[36:37] op_sel_hi:[1,0,1]
	v_pk_fma_f32 v[120:121], v[34:35], v[40:41], v[38:39] op_sel_hi:[1,0,1]
	s_waitcnt lgkmcnt(10)
	v_pk_mul_f32 v[64:65], v[64:65], v[108:109]
	v_pk_mul_f32 v[56:57], v[56:57], v[108:109]
	v_pk_fma_f32 v[64:65], v[66:67], v[120:121], v[64:65]
	s_waitcnt lgkmcnt(6)
	v_pk_fma_f32 v[56:57], v[60:61], v[106:107], v[56:57] op_sel_hi:[1,0,1]
	v_add_f32_e32 v64, v64, v65
	v_pk_mul_f32 v[58:59], v[58:59], v[120:121]
	v_pk_mul_f32 v[28:29], v[28:29], v[108:109]
	v_add_f32_dpp v60, v64, v64 quad_perm:[1,0,3,2] row_mask:0xf bank_mask:0xf bound_ctrl:1
	v_pk_fma_f32 v[58:59], v[62:63], v[106:107], v[58:59] op_sel_hi:[1,0,1]
	v_pk_fma_f32 v[28:29], v[30:31], v[120:121], v[28:29]
	v_add_f32_dpp v60, v60, v60 quad_perm:[2,3,0,1] row_mask:0xf bank_mask:0xf bound_ctrl:1
	v_add_f32_e32 v118, v28, v29
	ds_read_b128 v[28:31], v96 offset:12096
	ds_read_b128 v[32:35], v96 offset:12352
	ds_read_b128 v[36:39], v96 offset:12608
	ds_read_b128 v[40:43], v96 offset:12864
	v_add_f32_dpp v60, v60, v60 row_half_mirror row_mask:0xf bank_mask:0xf bound_ctrl:1
	ds_read_b128 v[44:47], v96 offset:13120
	ds_read_b32 v104, v91 offset:13376
	v_add_f32_dpp v60, v60, v60 row_mirror row_mask:0xf bank_mask:0xf bound_ctrl:1
	v_pk_fma_f32 v[106:107], v[52:53], v[60:61], v[56:57] op_sel_hi:[1,0,1]
	v_pk_fma_f32 v[108:109], v[54:55], v[60:61], v[58:59] op_sel_hi:[1,0,1]
	s_waitcnt lgkmcnt(10)
	v_pk_mul_f32 v[12:13], v[12:13], v[106:107]
	v_pk_mul_f32 v[8:9], v[8:9], v[106:107]
	v_pk_fma_f32 v[12:13], v[14:15], v[108:109], v[12:13]
	s_waitcnt lgkmcnt(6)
; DEVI float allreduce16(float v) {
;   v = dpp_add<0xB1>(v);
;   v = dpp_add<0x4E>(v);
;   v = dpp_add<0x141>(v);
;   v = dpp_add<0x140>(v);
;   return v;
; }
	v_pk_fma_f32 v[8:9], v[20:21], v[102:103], v[8:9] op_sel_hi:[1,0,1]
	v_add_f32_e32 v12, v12, v13
	v_pk_mul_f32 v[10:11], v[10:11], v[108:109]
	v_pk_mul_f32 v[48:49], v[48:49], v[106:107]
	v_add_f32_dpp v12, v12, v12 quad_perm:[1,0,3,2] row_mask:0xf bank_mask:0xf bound_ctrl:1
	v_pk_fma_f32 v[10:11], v[22:23], v[102:103], v[10:11] op_sel_hi:[1,0,1]
	v_pk_fma_f32 v[48:49], v[50:51], v[108:109], v[48:49]
	v_add_f32_dpp v12, v12, v12 quad_perm:[2,3,0,1] row_mask:0xf bank_mask:0xf bound_ctrl:1
	v_add_f32_e32 v119, v48, v49
	ds_read_b128 v[48:51], v96 offset:13440
	ds_read_b128 v[52:55], v96 offset:13696
	ds_read_b128 v[56:59], v96 offset:13952
	ds_read_b128 v[60:63], v96 offset:14208
	ds_read_b128 v[64:67], v96 offset:14464
	ds_read_b32 v110, v91 offset:14720
	v_add_f32_dpp v12, v12, v12 row_half_mirror row_mask:0xf bank_mask:0xf bound_ctrl:1
	ds_read_b128 v[106:109], v96 offset:14784
	ds_read_b128 v[124:127], v96 offset:15040
	ds_read_b128 v[128:131], v96 offset:15296
	ds_read_b128 v[132:135], v96 offset:15552
	ds_read_b128 v[136:139], v96 offset:15808
	ds_read_b32 v170, v91 offset:16064
	v_add_f32_dpp v12, v12, v12 row_mirror row_mask:0xf bank_mask:0xf bound_ctrl:1
	v_pk_fma_f32 v[8:9], v[16:17], v[12:13], v[8:9] op_sel_hi:[1,0,1]
	v_pk_fma_f32 v[10:11], v[18:19], v[12:13], v[10:11] op_sel_hi:[1,0,1]
	v_pk_mul_f32 v[12:13], v[24:25], v[8:9]
	v_pk_fma_f32 v[12:13], v[26:27], v[10:11], v[12:13]
	s_nop 0
	v_add_f32_e32 v120, v12, v13
	s_waitcnt lgkmcnt(8)
	v_pk_mul_f32 v[12:13], v[32:33], v[8:9]
	v_pk_mul_f32 v[8:9], v[28:29], v[8:9]
	v_pk_fma_f32 v[12:13], v[34:35], v[10:11], v[12:13]
	v_pk_fma_f32 v[8:9], v[40:41], v[104:105], v[8:9] op_sel_hi:[1,0,1]
	v_add_f32_e32 v12, v12, v13
	v_pk_mul_f32 v[10:11], v[30:31], v[10:11]
	ds_read_b128 v[140:143], v96 offset:16128
	v_add_f32_dpp v12, v12, v12 quad_perm:[1,0,3,2] row_mask:0xf bank_mask:0xf bound_ctrl:1
	v_pk_fma_f32 v[10:11], v[42:43], v[104:105], v[10:11] op_sel_hi:[1,0,1]
	ds_read_b128 v[144:147], v96 offset:16384
	v_add_f32_dpp v12, v12, v12 quad_perm:[2,3,0,1] row_mask:0xf bank_mask:0xf bound_ctrl:1
	ds_read_b128 v[148:151], v96 offset:16640
	ds_read_b128 v[152:155], v96 offset:16896
	v_add_f32_dpp v12, v12, v12 row_half_mirror row_mask:0xf bank_mask:0xf bound_ctrl:1
	ds_read_b128 v[156:159], v96 offset:17152
	ds_read_b32 v172, v91 offset:17408
	v_add_f32_dpp v12, v12, v12 row_mirror row_mask:0xf bank_mask:0xf bound_ctrl:1
	v_pk_fma_f32 v[8:9], v[36:37], v[12:13], v[8:9] op_sel_hi:[1,0,1]
	v_pk_fma_f32 v[10:11], v[38:39], v[12:13], v[10:11] op_sel_hi:[1,0,1]
	v_pk_mul_f32 v[12:13], v[44:45], v[8:9]
	s_nop 0
	v_pk_fma_f32 v[12:13], v[46:47], v[10:11], v[12:13]
	s_nop 0
	v_add_f32_e32 v121, v12, v13
	v_pk_mul_f32 v[12:13], v[52:53], v[8:9]
	v_pk_mul_f32 v[8:9], v[48:49], v[8:9]
	v_pk_fma_f32 v[12:13], v[54:55], v[10:11], v[12:13]
	s_waitcnt lgkmcnt(12)
	v_pk_fma_f32 v[8:9], v[60:61], v[110:111], v[8:9] op_sel_hi:[1,0,1]
	v_add_f32_e32 v12, v12, v13
	v_pk_mul_f32 v[10:11], v[50:51], v[10:11]
	s_nop 0
	v_add_f32_dpp v12, v12, v12 quad_perm:[1,0,3,2] row_mask:0xf bank_mask:0xf bound_ctrl:1
	v_pk_fma_f32 v[10:11], v[62:63], v[110:111], v[10:11] op_sel_hi:[1,0,1]
	s_nop 0
	v_add_f32_dpp v12, v12, v12 quad_perm:[2,3,0,1] row_mask:0xf bank_mask:0xf bound_ctrl:1
	s_nop 1
	v_add_f32_dpp v12, v12, v12 row_half_mirror row_mask:0xf bank_mask:0xf bound_ctrl:1
	s_nop 1
	v_add_f32_dpp v12, v12, v12 row_mirror row_mask:0xf bank_mask:0xf bound_ctrl:1
	v_pk_fma_f32 v[28:29], v[56:57], v[12:13], v[8:9] op_sel_hi:[1,0,1]
	v_pk_fma_f32 v[30:31], v[58:59], v[12:13], v[10:11] op_sel_hi:[1,0,1]
	s_waitcnt lgkmcnt(10)
	v_pk_mul_f32 v[32:33], v[124:125], v[28:29]
	v_pk_mul_f32 v[8:9], v[64:65], v[28:29]
	v_pk_fma_f32 v[32:33], v[126:127], v[30:31], v[32:33]
	v_pk_mul_f32 v[28:29], v[106:107], v[28:29]
	v_add_f32_e32 v32, v32, v33
	v_pk_fma_f32 v[8:9], v[66:67], v[30:31], v[8:9]
	s_waitcnt lgkmcnt(6)
	v_pk_fma_f32 v[28:29], v[132:133], v[170:171], v[28:29] op_sel_hi:[1,0,1]
	v_add_f32_dpp v32, v32, v32 quad_perm:[1,0,3,2] row_mask:0xf bank_mask:0xf bound_ctrl:1
	v_pk_mul_f32 v[30:31], v[108:109], v[30:31]
	v_add_f32_e32 v122, v8, v9
	v_add_f32_dpp v32, v32, v32 quad_perm:[2,3,0,1] row_mask:0xf bank_mask:0xf bound_ctrl:1
	v_pk_fma_f32 v[30:31], v[134:135], v[170:171], v[30:31] op_sel_hi:[1,0,1]
	ds_read_b128 v[16:19], v96 offset:17472
	ds_read_b128 v[24:27], v96 offset:17728
	ds_read_b128 v[12:15], v96 offset:17984
	ds_read_b128 v[20:23], v96 offset:18240
	v_add_f32_dpp v32, v32, v32 row_half_mirror row_mask:0xf bank_mask:0xf bound_ctrl:1
	ds_read_b128 v[8:11], v96 offset:18496
	ds_read_b32 v102, v91 offset:18752
	v_add_f32_dpp v32, v32, v32 row_mirror row_mask:0xf bank_mask:0xf bound_ctrl:1
	v_pk_fma_f32 v[48:49], v[128:129], v[32:33], v[28:29] op_sel_hi:[1,0,1]
	v_pk_fma_f32 v[50:51], v[130:131], v[32:33], v[30:31] op_sel_hi:[1,0,1]
	s_waitcnt lgkmcnt(10)
	v_pk_mul_f32 v[52:53], v[144:145], v[48:49]
	v_pk_mul_f32 v[28:29], v[136:137], v[48:49]
	v_pk_fma_f32 v[52:53], v[146:147], v[50:51], v[52:53]
	v_pk_mul_f32 v[48:49], v[140:141], v[48:49]
	v_add_f32_e32 v52, v52, v53
	v_pk_fma_f32 v[28:29], v[138:139], v[50:51], v[28:29]
	s_waitcnt lgkmcnt(6)
	v_pk_fma_f32 v[48:49], v[152:153], v[172:173], v[48:49] op_sel_hi:[1,0,1]
	v_add_f32_dpp v52, v52, v52 quad_perm:[1,0,3,2] row_mask:0xf bank_mask:0xf bound_ctrl:1
	v_pk_mul_f32 v[50:51], v[142:143], v[50:51]
	v_add_f32_e32 v123, v28, v29
	v_add_f32_dpp v52, v52, v52 quad_perm:[2,3,0,1] row_mask:0xf bank_mask:0xf bound_ctrl:1
	v_pk_fma_f32 v[50:51], v[154:155], v[172:173], v[50:51] op_sel_hi:[1,0,1]
	ds_read_b128 v[36:39], v96 offset:18816
	ds_read_b128 v[44:47], v96 offset:19072
	ds_read_b128 v[32:35], v96 offset:19328
	ds_read_b128 v[40:43], v96 offset:19584
	v_add_f32_dpp v52, v52, v52 row_half_mirror row_mask:0xf bank_mask:0xf bound_ctrl:1
	ds_read_b128 v[28:31], v96 offset:19840
	ds_read_b32 v104, v91 offset:20096
	v_add_f32_dpp v52, v52, v52 row_mirror row_mask:0xf bank_mask:0xf bound_ctrl:1
	v_pk_fma_f32 v[108:109], v[148:149], v[52:53], v[48:49] op_sel_hi:[1,0,1]
	v_pk_fma_f32 v[106:107], v[150:151], v[52:53], v[50:51] op_sel_hi:[1,0,1]
	s_waitcnt lgkmcnt(10)
	v_pk_mul_f32 v[24:25], v[24:25], v[108:109]
	v_pk_mul_f32 v[16:17], v[16:17], v[108:109]
	v_pk_fma_f32 v[24:25], v[26:27], v[106:107], v[24:25]
	s_waitcnt lgkmcnt(6)
	v_pk_fma_f32 v[16:17], v[20:21], v[102:103], v[16:17] op_sel_hi:[1,0,1]
	v_add_f32_e32 v24, v24, v25
	v_pk_mul_f32 v[18:19], v[18:19], v[106:107]
	v_pk_mul_f32 v[48:49], v[156:157], v[108:109]
	v_add_f32_dpp v20, v24, v24 quad_perm:[1,0,3,2] row_mask:0xf bank_mask:0xf bound_ctrl:1
	v_pk_fma_f32 v[18:19], v[22:23], v[102:103], v[18:19] op_sel_hi:[1,0,1]
	v_pk_fma_f32 v[48:49], v[158:159], v[106:107], v[48:49]
	v_add_f32_dpp v20, v20, v20 quad_perm:[2,3,0,1] row_mask:0xf bank_mask:0xf bound_ctrl:1
	v_add_f32_e32 v124, v48, v49
	ds_read_b128 v[56:59], v96 offset:20160
	v_add_f32_dpp v20, v20, v20 row_half_mirror row_mask:0xf bank_mask:0xf bound_ctrl:1
	ds_read_b128 v[64:67], v96 offset:20416
	ds_read_b128 v[52:55], v96 offset:20672
	v_add_f32_dpp v20, v20, v20 row_mirror row_mask:0xf bank_mask:0xf bound_ctrl:1
	v_pk_fma_f32 v[12:13], v[12:13], v[20:21], v[16:17] op_sel_hi:[1,0,1]
	v_pk_fma_f32 v[14:15], v[14:15], v[20:21], v[18:19] op_sel_hi:[1,0,1]
	v_pk_mul_f32 v[8:9], v[8:9], v[12:13]
	v_cndmask_b32_e64 v18, v115, v122, s[42:43]
	v_pk_fma_f32 v[8:9], v[10:11], v[14:15], v[8:9]
	s_waitcnt lgkmcnt(8)
	v_pk_mul_f32 v[10:11], v[38:39], v[14:15]
	v_add_f32_e32 v16, v8, v9
	s_waitcnt lgkmcnt(7)
	v_pk_mul_f32 v[8:9], v[44:45], v[12:13]
	s_waitcnt lgkmcnt(3)
	v_pk_fma_f32 v[10:11], v[42:43], v[104:105], v[10:11] op_sel_hi:[1,0,1]
	v_pk_fma_f32 v[8:9], v[46:47], v[14:15], v[8:9]
	v_cndmask_b32_e64 v15, v113, v120, s[42:43]
	v_add_f32_e32 v17, v8, v9
	v_pk_mul_f32 v[8:9], v[36:37], v[12:13]
	v_cndmask_b32_e64 v19, v116, v123, s[42:43]
	v_add_f32_dpp v12, v17, v17 quad_perm:[1,0,3,2] row_mask:0xf bank_mask:0xf bound_ctrl:1
	v_pk_fma_f32 v[8:9], v[40:41], v[104:105], v[8:9] op_sel_hi:[1,0,1]
	v_cndmask_b32_e64 v17, v114, v121, s[42:43]
	v_add_f32_dpp v12, v12, v12 quad_perm:[2,3,0,1] row_mask:0xf bank_mask:0xf bound_ctrl:1
	v_cndmask_b32_e64 v20, v117, v124, s[42:43]
	ds_read_b128 v[60:63], v96 offset:20928
	v_add_f32_dpp v12, v12, v12 row_half_mirror row_mask:0xf bank_mask:0xf bound_ctrl:1
	ds_read_b128 v[48:51], v96 offset:21184
	ds_read_b32 v110, v91 offset:21440
	v_add_f32_dpp v12, v12, v12 row_mirror row_mask:0xf bank_mask:0xf bound_ctrl:1
	v_pk_fma_f32 v[8:9], v[32:33], v[12:13], v[8:9] op_sel_hi:[1,0,1]
	v_pk_fma_f32 v[10:11], v[34:35], v[12:13], v[10:11] op_sel_hi:[1,0,1]
	v_pk_mul_f32 v[12:13], v[28:29], v[8:9]
	s_waitcnt vmcnt(3)
	v_lshlrev_b32_e32 v28, 16, v84
	v_pk_fma_f32 v[12:13], v[30:31], v[10:11], v[12:13]
	v_and_b32_e32 v29, 0xffff0000, v84
	v_add_f32_e32 v14, v12, v13
	s_waitcnt lgkmcnt(4)
	v_pk_mul_f32 v[12:13], v[64:65], v[8:9]
	v_pk_mul_f32 v[8:9], v[56:57], v[8:9]
	v_pk_fma_f32 v[12:13], v[66:67], v[10:11], v[12:13]
	s_waitcnt lgkmcnt(0)
	v_pk_fma_f32 v[8:9], v[60:61], v[110:111], v[8:9] op_sel_hi:[1,0,1]
	v_add_f32_e32 v12, v12, v13
	v_pk_mul_f32 v[10:11], v[58:59], v[10:11]
	s_waitcnt vmcnt(1)
	v_cvt_f32_f16_sdwa v31, v88 dst_sel:DWORD dst_unused:UNUSED_PAD src0_sel:WORD_1
	v_add_f32_dpp v12, v12, v12 quad_perm:[1,0,3,2] row_mask:0xf bank_mask:0xf bound_ctrl:1
	v_pk_fma_f32 v[10:11], v[62:63], v[110:111], v[10:11] op_sel_hi:[1,0,1]
	v_cvt_f32_f16_e32 v30, v88
	v_add_f32_dpp v12, v12, v12 quad_perm:[2,3,0,1] row_mask:0xf bank_mask:0xf bound_ctrl:1
	v_cvt_f32_f16_sdwa v35, v89 dst_sel:DWORD dst_unused:UNUSED_PAD src0_sel:WORD_1
	v_cvt_f32_f16_e32 v34, v89
	v_add_f32_dpp v12, v12, v12 row_half_mirror row_mask:0xf bank_mask:0xf bound_ctrl:1
	v_lshlrev_b32_e32 v32, 16, v85
	v_and_b32_e32 v33, 0xffff0000, v85
	v_add_f32_dpp v12, v12, v12 row_mirror row_mask:0xf bank_mask:0xf bound_ctrl:1
	v_pk_fma_f32 v[8:9], v[52:53], v[12:13], v[8:9] op_sel_hi:[1,0,1]
	v_pk_fma_f32 v[10:11], v[54:55], v[12:13], v[10:11] op_sel_hi:[1,0,1]
	v_pk_mul_f32 v[12:13], v[48:49], v[8:9]
	v_pk_mul_f32 v[22:23], v[2:3], v[32:33]
	v_pk_fma_f32 v[12:13], v[50:51], v[10:11], v[12:13]
	s_waitcnt vmcnt(0)
; DEVI void scan_item(const Params& p, int l, int item, unsigned char* smem) {
;     ...
;   constexpr int NCH = NKEY / SC_TOK;
;   SC_LOAD(0, RA);
;   SC_LOAD(1, RB);
;   SC_STAGE(0, RA);
;   __syncthreads();
;   f32x2 S01 = {0.f, 0.f}, S23 = {0.f, 0.f};
;   const int vidx = 320 + wave * 4 + rl;
;   const bool bit3 = (kl & 8) != 0, bit2 = (kl & 4) != 0, bit1 = (kl & 2) != 0, bit0 = (kl & 1) != 0;
;   __builtin_amdgcn_s_setprio(3);
;   for (int c = 0; c < NCH; c += 2) {
;     const bool more = (c + 2 < NCH);
;     if (more) SC_LOAD(c + 2, RA);
;     SC_CHUNK(0);
;     SC_STAGE(1, RB);
;     __syncthreads();
;     SC_YOUT(c, 0);
;     if (more) SC_LOAD(c + 3, RB);
	v_pk_mul_f32 v[22:23], v[90:91], v[22:23] op_sel_hi:[0,1]
	v_add_f32_e32 v12, v12, v13
	v_cndmask_b32_e64 v13, v120, v113, s[42:43]
	v_pk_mul_f32 v[26:27], v[34:35], v[22:23] neg_lo:[0,1] neg_hi:[0,1]
	v_pk_add_f32 v[34:35], v[34:35], -1.0 op_sel_hi:[1,0]
	v_add_f32_dpp v13, v15, v13 row_ror:8 row_mask:0xf bank_mask:0xf bound_ctrl:1
	v_cndmask_b32_e64 v15, v121, v114, s[42:43]
	v_pk_fma_f32 v[34:35], v[6:7], v[34:35], 1.0 op_sel_hi:[1,1,0]
	s_nop 0
	v_add_f32_dpp v15, v17, v15 row_ror:8 row_mask:0xf bank_mask:0xf bound_ctrl:1
	v_cndmask_b32_e64 v17, v122, v115, s[42:43]
	s_nop 1
	v_add_f32_dpp v17, v18, v17 row_ror:8 row_mask:0xf bank_mask:0xf bound_ctrl:1
	v_cndmask_b32_e64 v18, v123, v116, s[42:43]
	s_nop 1
	v_add_f32_dpp v18, v19, v18 row_ror:8 row_mask:0xf bank_mask:0xf bound_ctrl:1
	v_cndmask_b32_e64 v19, v124, v117, s[42:43]
	s_nop 1
	v_add_f32_dpp v19, v20, v19 row_ror:8 row_mask:0xf bank_mask:0xf bound_ctrl:1
	v_cndmask_b32_e64 v20, v16, v111, s[42:43]
	v_cndmask_b32_e64 v16, v111, v16, s[42:43]
	s_nop 1
	v_add_f32_dpp v16, v16, v20 row_ror:8 row_mask:0xf bank_mask:0xf bound_ctrl:1
	v_cndmask_b32_e64 v20, v14, v118, s[42:43]
	v_cndmask_b32_e64 v14, v118, v14, s[42:43]
	s_nop 1
	v_add_f32_dpp v14, v14, v20 row_ror:8 row_mask:0xf bank_mask:0xf bound_ctrl:1
	v_cndmask_b32_e64 v20, v12, v119, s[42:43]
	v_cndmask_b32_e64 v12, v119, v12, s[42:43]
	s_nop 1
	v_add_f32_dpp v12, v12, v20 row_ror:8 row_mask:0xf bank_mask:0xf bound_ctrl:1
	v_cndmask_b32_e64 v20, v19, v13, s[44:45]
	v_cndmask_b32_e64 v13, v13, v19, s[44:45]
	v_cndmask_b32_e64 v19, v16, v15, s[44:45]
	v_cndmask_b32_e64 v15, v15, v16, s[44:45]
	v_cndmask_b32_e64 v16, v14, v17, s[44:45]
	v_cndmask_b32_e64 v14, v17, v14, s[44:45]
	v_add_f32_dpp v13, v13, v20 row_half_mirror row_mask:0xf bank_mask:0xf bound_ctrl:1
	v_add_f32_dpp v15, v15, v19 row_half_mirror row_mask:0xf bank_mask:0xf bound_ctrl:1
	v_add_f32_dpp v14, v14, v16 row_half_mirror row_mask:0xf bank_mask:0xf bound_ctrl:1
	v_cndmask_b32_e64 v16, v12, v18, s[44:45]
	v_cndmask_b32_e64 v12, v18, v12, s[44:45]
	v_pk_mul_f32 v[18:19], v[0:1], v[28:29]
	v_cvt_f32_f16_sdwa v17, v86 dst_sel:DWORD dst_unused:UNUSED_PAD src0_sel:WORD_1
	v_add_f32_dpp v12, v12, v16 row_half_mirror row_mask:0xf bank_mask:0xf bound_ctrl:1
	v_cndmask_b32_e64 v16, v14, v13, s[46:47]
	v_cndmask_b32_e64 v13, v13, v14, s[46:47]
	v_pk_mul_f32 v[20:21], v[90:91], v[18:19] op_sel_hi:[0,1]
	v_cvt_f32_f16_e32 v18, v87
	v_add_f32_dpp v13, v13, v16 quad_perm:[2,3,0,1] row_mask:0xf bank_mask:0xf bound_ctrl:1
	v_cvt_f32_f16_e32 v16, v86
	v_cvt_f32_f16_sdwa v19, v87 dst_sel:DWORD dst_unused:UNUSED_PAD src0_sel:WORD_1
	v_mul_f32_e32 v17, 0x3fb8aa3b, v17
	v_mul_f32_e32 v18, 0x3fb8aa3b, v18
	v_mul_f32_e32 v16, 0x3fb8aa3b, v16
	v_mul_f32_e32 v19, 0x3fb8aa3b, v19
	v_cndmask_b32_e64 v14, v12, v15, s[46:47]
	v_cndmask_b32_e64 v12, v15, v12, s[46:47]
	v_exp_f32_e32 v16, v16
	v_exp_f32_e32 v17, v17
	v_exp_f32_e32 v18, v18
	v_exp_f32_e32 v19, v19
	v_add_f32_dpp v12, v12, v14 quad_perm:[2,3,0,1] row_mask:0xf bank_mask:0xf bound_ctrl:1
	v_cndmask_b32_e64 v14, v12, v13, s[48:49]
	v_cndmask_b32_e64 v12, v13, v12, s[48:49]
	v_pk_mul_f32 v[24:25], v[30:31], v[20:21] neg_lo:[0,1] neg_hi:[0,1]
	v_pk_add_f32 v[30:31], v[30:31], -1.0 op_sel_hi:[1,0]
	v_add_f32_dpp v12, v12, v14 quad_perm:[1,0,3,2] row_mask:0xf bank_mask:0xf bound_ctrl:1
	v_pk_fma_f32 v[36:37], v[4:5], v[30:31], 1.0 op_sel_hi:[1,1,0]
	ds_write_b32 v97, v12 offset:43008
	v_lshlrev_b32_e32 v12, 16, v82
	v_and_b32_e32 v13, 0xffff0000, v82
	v_lshlrev_b32_e32 v14, 16, v83
	v_and_b32_e32 v15, 0xffff0000, v83
	v_pk_mul_f32 v[30:31], v[34:35], v[32:33]
	v_pk_mul_f32 v[28:29], v[36:37], v[28:29]
	ds_write_b128 v98, v[16:19]
	ds_write_b128 v98, v[20:23] offset:256
	ds_write_b128 v98, v[24:27] offset:512
	ds_write_b128 v98, v[28:31] offset:768
	ds_write_b128 v98, v[12:15] offset:1024
	s_and_saveexec_b64 s[50:51], s[40:41]
	v_lshlrev_b32_e32 v12, 16, v80
	v_and_b32_e32 v13, 0xffff0000, v80
	v_lshlrev_b32_e32 v14, 16, v81
	v_and_b32_e32 v15, 0xffff0000, v81
	ds_write_b128 v98, v[12:15] offset:1280
	s_or_b64 exec, exec, s[50:51]
	v_subrev_u32_e32 v12, 48, v112
	v_cmp_gt_i32_e32 vcc, s92, v12
	v_add_u32_e32 v13, 0xfffffed0, v112
	v_mov_b32_e32 v15, s36
	v_cndmask_b32_e32 v14, v226, v227, vcc
	v_cndmask_b32_e32 v12, v13, v12, vcc
	v_mov_b32_e32 v13, s27
	v_add_u32_e32 v14, v14, v105
	v_cndmask_b32_e32 v13, v13, v15, vcc
	v_cndmask_b32_e64 v12, v14, v12, s[38:39]
	s_waitcnt lgkmcnt(0)
	s_barrier
	v_add_u32_e32 v12, v12, v13
	ds_read_b32 v13, v99 offset:43008
	s_mov_b32 s2, 0x3d800000
	s_andn2_b64 vcc, exec, s[90:91]
	s_waitcnt lgkmcnt(0)
	v_fma_mixlo_f16 v14, v13, s2, 0
	v_ashrrev_i32_e32 v13, 31, v12
	v_lshlrev_b64 v[12:13], 10, v[12:13]
	v_lshl_add_u64 v[12:13], v[100:101], 0, v[12:13]
	global_store_short v[12:13], v14, off
	v_cndmask_b32_e64 v12, 0, 1, s[90:91]
	v_cmp_ne_u32_e64 s[50:51], 1, v12
	s_cbranch_vccnz .LBB0_205
	v_cmp_gt_i32_e32 vcc, s92, v112
	v_add_u32_e32 v12, 0xffffff00, v112
	s_movk_i32 s2, 0xffd0
	v_cndmask_b32_e32 v13, v226, v227, vcc
	v_cndmask_b32_e32 v12, v12, v112, vcc
	v_mov_b32_e32 v14, s27
	v_mov_b32_e32 v15, s36
	v_add3_u32 v13, v13, v105, s2
	v_cndmask_b32_e32 v14, v14, v15, vcc
	v_cndmask_b32_e64 v12, v13, v12, s[38:39]
	v_add_u32_e32 v12, v12, v14
	v_mov_b64_e32 v[14:15], s[22:23]
	v_mad_i64_i32 v[14:15], s[90:91], v12, s3, v[14:15]
	v_lshl_add_u64 v[16:17], v[14:15], 0, v[162:163]
	global_load_dwordx2 v[82:83], v[16:17], off
	global_load_dwordx2 v[84:85], v[16:17], off offset:1024
	s_and_saveexec_b64 s[90:91], s[40:41]
	s_cbranch_execz .LBB0_204
	s_lshl_b32 s96, s26, 1
	v_lshl_add_u64 v[14:15], v[14:15], 0, s[96:97]
	v_lshl_add_u64 v[14:15], v[14:15], 0, v[162:163]
	global_load_dwordx2 v[80:81], v[14:15], off offset:2048

.LBB0_205:
	ds_read_b128 v[12:15], v103 offset:21504
	ds_read_b128 v[16:19], v103 offset:21760
	ds_read_b128 v[20:23], v103 offset:22016
	ds_read_b128 v[24:27], v103 offset:22272
	ds_read_b128 v[28:31], v103 offset:22528
	ds_read_b32 v102, v91 offset:22784
	ds_read_b128 v[32:35], v103 offset:22848
	ds_read_b128 v[36:39], v103 offset:23104
	ds_read_b128 v[40:43], v103 offset:23360
	ds_read_b128 v[44:47], v103 offset:23616
	ds_read_b128 v[48:51], v103 offset:23872
	ds_read_b32 v104, v91 offset:24128
	ds_read_b128 v[52:55], v103 offset:24192
	ds_read_b128 v[56:59], v103 offset:24448
	ds_read_b128 v[60:63], v103 offset:24704
	ds_read_b128 v[64:67], v103 offset:24960
	ds_read_b128 v[106:109], v103 offset:25216
	ds_read_b32 v110, v91 offset:25472
	s_waitcnt lgkmcnt(14)
	v_pk_mul_f32 v[16:17], v[8:9], v[16:17]
	s_and_b64 vcc, exec, s[50:51]
	v_pk_fma_f32 v[16:17], v[10:11], v[18:19], v[16:17]
	s_waitcnt lgkmcnt(12)
	v_pk_mul_f32 v[18:19], v[26:27], v[102:103] op_sel_hi:[1,0]
	v_add_f32_e32 v111, v16, v17
	v_pk_mul_f32 v[16:17], v[24:25], v[102:103] op_sel_hi:[1,0]
	v_pk_fma_f32 v[10:11], v[10:11], v[14:15], v[18:19]
	v_pk_fma_f32 v[8:9], v[8:9], v[12:13], v[16:17]
	v_add_f32_dpp v12, v111, v111 quad_perm:[1,0,3,2] row_mask:0xf bank_mask:0xf bound_ctrl:1
	s_nop 1
	v_add_f32_dpp v12, v12, v12 quad_perm:[2,3,0,1] row_mask:0xf bank_mask:0xf bound_ctrl:1
	s_nop 1
	v_add_f32_dpp v12, v12, v12 row_half_mirror row_mask:0xf bank_mask:0xf bound_ctrl:1
	s_nop 1
	v_add_f32_dpp v12, v12, v12 row_mirror row_mask:0xf bank_mask:0xf bound_ctrl:1
	v_pk_fma_f32 v[8:9], v[20:21], v[12:13], v[8:9] op_sel_hi:[1,0,1]
	v_pk_fma_f32 v[10:11], v[22:23], v[12:13], v[10:11] op_sel_hi:[1,0,1]
	v_pk_mul_f32 v[12:13], v[28:29], v[8:9]
	s_nop 0
	v_pk_fma_f32 v[12:13], v[30:31], v[10:11], v[12:13]
	v_add_f32_e32 v113, v12, v13
	s_waitcnt lgkmcnt(8)
	v_pk_mul_f32 v[12:13], v[36:37], v[8:9]
	v_pk_mul_f32 v[8:9], v[32:33], v[8:9]
	v_pk_fma_f32 v[12:13], v[38:39], v[10:11], v[12:13]
	s_waitcnt lgkmcnt(6)
	v_pk_fma_f32 v[8:9], v[44:45], v[104:105], v[8:9] op_sel_hi:[1,0,1]
	v_add_f32_e32 v12, v12, v13
	v_pk_mul_f32 v[10:11], v[34:35], v[10:11]
	ds_read_b128 v[28:31], v103 offset:25536
	v_add_f32_dpp v12, v12, v12 quad_perm:[1,0,3,2] row_mask:0xf bank_mask:0xf bound_ctrl:1
	v_pk_fma_f32 v[10:11], v[46:47], v[104:105], v[10:11] op_sel_hi:[1,0,1]
	ds_read_b128 v[116:119], v103 offset:25792
	v_add_f32_dpp v12, v12, v12 quad_perm:[2,3,0,1] row_mask:0xf bank_mask:0xf bound_ctrl:1
	ds_read_b128 v[120:123], v103 offset:26048
	ds_read_b128 v[124:127], v103 offset:26304
	v_add_f32_dpp v12, v12, v12 row_half_mirror row_mask:0xf bank_mask:0xf bound_ctrl:1
	ds_read_b128 v[128:131], v103 offset:26560
	ds_read_b32 v148, v91 offset:26816
	v_add_f32_dpp v12, v12, v12 row_mirror row_mask:0xf bank_mask:0xf bound_ctrl:1
	v_pk_fma_f32 v[8:9], v[40:41], v[12:13], v[8:9] op_sel_hi:[1,0,1]
	v_pk_fma_f32 v[10:11], v[42:43], v[12:13], v[10:11] op_sel_hi:[1,0,1]
	v_pk_mul_f32 v[12:13], v[48:49], v[8:9]
	s_nop 0
	v_pk_fma_f32 v[12:13], v[50:51], v[10:11], v[12:13]
	v_add_f32_e32 v114, v12, v13
	s_waitcnt lgkmcnt(8)
	v_pk_mul_f32 v[12:13], v[56:57], v[8:9]
	v_pk_mul_f32 v[8:9], v[52:53], v[8:9]
	v_pk_fma_f32 v[12:13], v[58:59], v[10:11], v[12:13]
	s_waitcnt lgkmcnt(6)
	v_pk_fma_f32 v[8:9], v[64:65], v[110:111], v[8:9] op_sel_hi:[1,0,1]
	v_add_f32_e32 v12, v12, v13
	v_pk_mul_f32 v[10:11], v[54:55], v[10:11]
	ds_read_b128 v[48:51], v103 offset:26880
	v_add_f32_dpp v12, v12, v12 quad_perm:[1,0,3,2] row_mask:0xf bank_mask:0xf bound_ctrl:1
	v_pk_fma_f32 v[10:11], v[66:67], v[110:111], v[10:11] op_sel_hi:[1,0,1]
	ds_read_b128 v[132:135], v103 offset:27136
	v_add_f32_dpp v12, v12, v12 quad_perm:[2,3,0,1] row_mask:0xf bank_mask:0xf bound_ctrl:1
	ds_read_b128 v[136:139], v103 offset:27392
	ds_read_b128 v[140:143], v103 offset:27648
	v_add_f32_dpp v12, v12, v12 row_half_mirror row_mask:0xf bank_mask:0xf bound_ctrl:1
	ds_read_b128 v[144:147], v103 offset:27904
	ds_read_b32 v150, v91 offset:28160
	v_add_f32_dpp v12, v12, v12 row_mirror row_mask:0xf bank_mask:0xf bound_ctrl:1
	v_pk_fma_f32 v[32:33], v[60:61], v[12:13], v[8:9] op_sel_hi:[1,0,1]
	v_pk_fma_f32 v[34:35], v[62:63], v[12:13], v[10:11] op_sel_hi:[1,0,1]
	s_waitcnt lgkmcnt(10)
	v_pk_mul_f32 v[36:37], v[116:117], v[32:33]
	v_pk_mul_f32 v[8:9], v[106:107], v[32:33]
	v_pk_fma_f32 v[36:37], v[118:119], v[34:35], v[36:37]
	v_pk_mul_f32 v[28:29], v[28:29], v[32:33]
	v_add_f32_e32 v36, v36, v37
	s_waitcnt lgkmcnt(6)
	v_pk_fma_f32 v[28:29], v[124:125], v[148:149], v[28:29] op_sel_hi:[1,0,1]
	v_pk_mul_f32 v[30:31], v[30:31], v[34:35]
	v_add_f32_dpp v32, v36, v36 quad_perm:[1,0,3,2] row_mask:0xf bank_mask:0xf bound_ctrl:1
	v_pk_fma_f32 v[30:31], v[126:127], v[148:149], v[30:31] op_sel_hi:[1,0,1]
	v_pk_fma_f32 v[8:9], v[108:109], v[34:35], v[8:9]
	v_add_f32_dpp v32, v32, v32 quad_perm:[2,3,0,1] row_mask:0xf bank_mask:0xf bound_ctrl:1
	v_add_f32_e32 v115, v8, v9
	ds_read_b128 v[16:19], v103 offset:28224
	ds_read_b128 v[24:27], v103 offset:28480
	ds_read_b128 v[12:15], v103 offset:28736
	ds_read_b128 v[20:23], v103 offset:28992
	v_add_f32_dpp v32, v32, v32 row_half_mirror row_mask:0xf bank_mask:0xf bound_ctrl:1
	ds_read_b128 v[8:11], v103 offset:29248
	ds_read_b32 v102, v91 offset:29504
	v_add_f32_dpp v32, v32, v32 row_mirror row_mask:0xf bank_mask:0xf bound_ctrl:1
	v_pk_fma_f32 v[52:53], v[120:121], v[32:33], v[28:29] op_sel_hi:[1,0,1]
	v_pk_fma_f32 v[54:55], v[122:123], v[32:33], v[30:31] op_sel_hi:[1,0,1]
	s_waitcnt lgkmcnt(10)
	v_pk_mul_f32 v[56:57], v[132:133], v[52:53]
	v_pk_mul_f32 v[28:29], v[128:129], v[52:53]
	v_pk_fma_f32 v[56:57], v[134:135], v[54:55], v[56:57]
	v_pk_mul_f32 v[48:49], v[48:49], v[52:53]
	v_add_f32_e32 v56, v56, v57
	s_waitcnt lgkmcnt(6)
; DEVI float allreduce16(float v) {
;   v = dpp_add<0xB1>(v);
;   v = dpp_add<0x4E>(v);
;   v = dpp_add<0x141>(v);
;   v = dpp_add<0x140>(v);
;   return v;
; }
	v_pk_fma_f32 v[48:49], v[140:141], v[150:151], v[48:49] op_sel_hi:[1,0,1]
	v_pk_mul_f32 v[50:51], v[50:51], v[54:55]
	v_add_f32_dpp v52, v56, v56 quad_perm:[1,0,3,2] row_mask:0xf bank_mask:0xf bound_ctrl:1
	v_pk_fma_f32 v[50:51], v[142:143], v[150:151], v[50:51] op_sel_hi:[1,0,1]
	v_pk_fma_f32 v[28:29], v[130:131], v[54:55], v[28:29]
	v_add_f32_dpp v52, v52, v52 quad_perm:[2,3,0,1] row_mask:0xf bank_mask:0xf bound_ctrl:1
	v_add_f32_e32 v116, v28, v29
	ds_read_b128 v[36:39], v103 offset:29568
	ds_read_b128 v[44:47], v103 offset:29824
	ds_read_b128 v[32:35], v103 offset:30080
	ds_read_b128 v[40:43], v103 offset:30336
	v_add_f32_dpp v52, v52, v52 row_half_mirror row_mask:0xf bank_mask:0xf bound_ctrl:1
	ds_read_b128 v[28:31], v103 offset:30592
	ds_read_b32 v104, v91 offset:30848
	v_add_f32_dpp v52, v52, v52 row_mirror row_mask:0xf bank_mask:0xf bound_ctrl:1
	v_pk_fma_f32 v[110:111], v[136:137], v[52:53], v[48:49] op_sel_hi:[1,0,1]
	v_pk_fma_f32 v[108:109], v[138:139], v[52:53], v[50:51] op_sel_hi:[1,0,1]
	s_waitcnt lgkmcnt(10)
	v_pk_mul_f32 v[24:25], v[24:25], v[110:111]
	v_pk_mul_f32 v[16:17], v[16:17], v[110:111]
	v_pk_fma_f32 v[24:25], v[26:27], v[108:109], v[24:25]
	s_waitcnt lgkmcnt(6)
	v_pk_fma_f32 v[16:17], v[20:21], v[102:103], v[16:17] op_sel_hi:[1,0,1]
	v_add_f32_e32 v24, v24, v25
	v_pk_mul_f32 v[48:49], v[144:145], v[110:111]
	v_pk_mul_f32 v[18:19], v[18:19], v[108:109]
	v_add_f32_dpp v20, v24, v24 quad_perm:[1,0,3,2] row_mask:0xf bank_mask:0xf bound_ctrl:1
	v_pk_fma_f32 v[48:49], v[146:147], v[108:109], v[48:49]
	v_pk_fma_f32 v[18:19], v[22:23], v[102:103], v[18:19] op_sel_hi:[1,0,1]
	v_add_f32_dpp v20, v20, v20 quad_perm:[2,3,0,1] row_mask:0xf bank_mask:0xf bound_ctrl:1
	v_add_f32_e32 v117, v48, v49
	ds_read_b128 v[56:59], v103 offset:30912
	ds_read_b128 v[64:67], v103 offset:31168
	ds_read_b128 v[52:55], v103 offset:31424
	ds_read_b128 v[60:63], v103 offset:31680
	v_add_f32_dpp v20, v20, v20 row_half_mirror row_mask:0xf bank_mask:0xf bound_ctrl:1
	ds_read_b128 v[48:51], v103 offset:31936
	ds_read_b32 v106, v91 offset:32192
	v_add_f32_dpp v20, v20, v20 row_mirror row_mask:0xf bank_mask:0xf bound_ctrl:1
	v_pk_fma_f32 v[108:109], v[12:13], v[20:21], v[16:17] op_sel_hi:[1,0,1]
	v_pk_fma_f32 v[118:119], v[14:15], v[20:21], v[18:19] op_sel_hi:[1,0,1]
	s_waitcnt lgkmcnt(10)
	v_pk_mul_f32 v[44:45], v[44:45], v[108:109]
	v_pk_mul_f32 v[36:37], v[36:37], v[108:109]
	v_pk_fma_f32 v[44:45], v[46:47], v[118:119], v[44:45]
	s_waitcnt lgkmcnt(6)
	v_pk_fma_f32 v[36:37], v[40:41], v[104:105], v[36:37] op_sel_hi:[1,0,1]
	v_add_f32_e32 v44, v44, v45
	v_pk_mul_f32 v[38:39], v[38:39], v[118:119]
	v_pk_mul_f32 v[8:9], v[8:9], v[108:109]
	v_add_f32_dpp v40, v44, v44 quad_perm:[1,0,3,2] row_mask:0xf bank_mask:0xf bound_ctrl:1
	v_pk_fma_f32 v[38:39], v[42:43], v[104:105], v[38:39] op_sel_hi:[1,0,1]
	v_pk_fma_f32 v[8:9], v[10:11], v[118:119], v[8:9]
	v_add_f32_dpp v40, v40, v40 quad_perm:[2,3,0,1] row_mask:0xf bank_mask:0xf bound_ctrl:1
	v_add_f32_e32 v111, v8, v9
	ds_read_b128 v[8:11], v103 offset:32256
	ds_read_b128 v[12:15], v103 offset:32512
	ds_read_b128 v[16:19], v103 offset:32768
	ds_read_b128 v[20:23], v103 offset:33024
	v_add_f32_dpp v40, v40, v40 row_half_mirror row_mask:0xf bank_mask:0xf bound_ctrl:1
	ds_read_b128 v[24:27], v103 offset:33280
	ds_read_b32 v102, v91 offset:33536
	v_add_f32_dpp v40, v40, v40 row_mirror row_mask:0xf bank_mask:0xf bound_ctrl:1
	v_pk_fma_f32 v[108:109], v[32:33], v[40:41], v[36:37] op_sel_hi:[1,0,1]
	v_pk_fma_f32 v[120:121], v[34:35], v[40:41], v[38:39] op_sel_hi:[1,0,1]
	s_waitcnt lgkmcnt(10)
	v_pk_mul_f32 v[64:65], v[64:65], v[108:109]
	v_pk_mul_f32 v[56:57], v[56:57], v[108:109]
	v_pk_fma_f32 v[64:65], v[66:67], v[120:121], v[64:65]
	s_waitcnt lgkmcnt(6)
	v_pk_fma_f32 v[56:57], v[60:61], v[106:107], v[56:57] op_sel_hi:[1,0,1]
	v_add_f32_e32 v64, v64, v65
	v_pk_mul_f32 v[58:59], v[58:59], v[120:121]
	v_pk_mul_f32 v[28:29], v[28:29], v[108:109]
	v_add_f32_dpp v60, v64, v64 quad_perm:[1,0,3,2] row_mask:0xf bank_mask:0xf bound_ctrl:1
	v_pk_fma_f32 v[58:59], v[62:63], v[106:107], v[58:59] op_sel_hi:[1,0,1]
	v_pk_fma_f32 v[28:29], v[30:31], v[120:121], v[28:29]
	v_add_f32_dpp v60, v60, v60 quad_perm:[2,3,0,1] row_mask:0xf bank_mask:0xf bound_ctrl:1
	v_add_f32_e32 v118, v28, v29
	ds_read_b128 v[28:31], v103 offset:33600
	ds_read_b128 v[32:35], v103 offset:33856
	ds_read_b128 v[36:39], v103 offset:34112
	ds_read_b128 v[40:43], v103 offset:34368
	v_add_f32_dpp v60, v60, v60 row_half_mirror row_mask:0xf bank_mask:0xf bound_ctrl:1
	ds_read_b128 v[44:47], v103 offset:34624
	ds_read_b32 v104, v91 offset:34880
	v_add_f32_dpp v60, v60, v60 row_mirror row_mask:0xf bank_mask:0xf bound_ctrl:1
	v_pk_fma_f32 v[106:107], v[52:53], v[60:61], v[56:57] op_sel_hi:[1,0,1]
	v_pk_fma_f32 v[108:109], v[54:55], v[60:61], v[58:59] op_sel_hi:[1,0,1]
	s_waitcnt lgkmcnt(10)
	v_pk_mul_f32 v[12:13], v[12:13], v[106:107]
	v_pk_mul_f32 v[8:9], v[8:9], v[106:107]
	v_pk_fma_f32 v[12:13], v[14:15], v[108:109], v[12:13]
	s_waitcnt lgkmcnt(6)
; DEVI float allreduce16(float v) {
;   v = dpp_add<0xB1>(v);
;   v = dpp_add<0x4E>(v);
;   v = dpp_add<0x141>(v);
;   v = dpp_add<0x140>(v);
;   return v;
; }
	v_pk_fma_f32 v[8:9], v[20:21], v[102:103], v[8:9] op_sel_hi:[1,0,1]
	v_add_f32_e32 v12, v12, v13
	v_pk_mul_f32 v[10:11], v[10:11], v[108:109]
	v_pk_mul_f32 v[48:49], v[48:49], v[106:107]
	v_add_f32_dpp v12, v12, v12 quad_perm:[1,0,3,2] row_mask:0xf bank_mask:0xf bound_ctrl:1
	v_pk_fma_f32 v[10:11], v[22:23], v[102:103], v[10:11] op_sel_hi:[1,0,1]
	v_pk_fma_f32 v[48:49], v[50:51], v[108:109], v[48:49]
	v_add_f32_dpp v12, v12, v12 quad_perm:[2,3,0,1] row_mask:0xf bank_mask:0xf bound_ctrl:1
	v_add_f32_e32 v119, v48, v49
	ds_read_b128 v[48:51], v103 offset:34944
	ds_read_b128 v[52:55], v103 offset:35200
	ds_read_b128 v[56:59], v103 offset:35456
	ds_read_b128 v[60:63], v103 offset:35712
	ds_read_b128 v[64:67], v103 offset:35968
	ds_read_b32 v110, v91 offset:36224
	v_add_f32_dpp v12, v12, v12 row_half_mirror row_mask:0xf bank_mask:0xf bound_ctrl:1
	ds_read_b128 v[106:109], v103 offset:36288
	ds_read_b128 v[124:127], v103 offset:36544
	ds_read_b128 v[128:131], v103 offset:36800
	ds_read_b128 v[132:135], v103 offset:37056
	ds_read_b128 v[136:139], v103 offset:37312
	ds_read_b32 v170, v91 offset:37568
	v_add_f32_dpp v12, v12, v12 row_mirror row_mask:0xf bank_mask:0xf bound_ctrl:1
	v_pk_fma_f32 v[8:9], v[16:17], v[12:13], v[8:9] op_sel_hi:[1,0,1]
	v_pk_fma_f32 v[10:11], v[18:19], v[12:13], v[10:11] op_sel_hi:[1,0,1]
	v_pk_mul_f32 v[12:13], v[24:25], v[8:9]
	v_pk_fma_f32 v[12:13], v[26:27], v[10:11], v[12:13]
	s_nop 0
	v_add_f32_e32 v120, v12, v13
	s_waitcnt lgkmcnt(8)
	v_pk_mul_f32 v[12:13], v[32:33], v[8:9]
	v_pk_mul_f32 v[8:9], v[28:29], v[8:9]
	v_pk_fma_f32 v[12:13], v[34:35], v[10:11], v[12:13]
	v_pk_fma_f32 v[8:9], v[40:41], v[104:105], v[8:9] op_sel_hi:[1,0,1]
	v_add_f32_e32 v12, v12, v13
	v_pk_mul_f32 v[10:11], v[30:31], v[10:11]
	ds_read_b128 v[140:143], v103 offset:37632
	v_add_f32_dpp v12, v12, v12 quad_perm:[1,0,3,2] row_mask:0xf bank_mask:0xf bound_ctrl:1
	v_pk_fma_f32 v[10:11], v[42:43], v[104:105], v[10:11] op_sel_hi:[1,0,1]
	ds_read_b128 v[144:147], v103 offset:37888
	v_add_f32_dpp v12, v12, v12 quad_perm:[2,3,0,1] row_mask:0xf bank_mask:0xf bound_ctrl:1
	ds_read_b128 v[148:151], v103 offset:38144
	ds_read_b128 v[152:155], v103 offset:38400
	v_add_f32_dpp v12, v12, v12 row_half_mirror row_mask:0xf bank_mask:0xf bound_ctrl:1
	ds_read_b128 v[156:159], v103 offset:38656
	ds_read_b32 v172, v91 offset:38912
	v_add_f32_dpp v12, v12, v12 row_mirror row_mask:0xf bank_mask:0xf bound_ctrl:1
	v_pk_fma_f32 v[8:9], v[36:37], v[12:13], v[8:9] op_sel_hi:[1,0,1]
	v_pk_fma_f32 v[10:11], v[38:39], v[12:13], v[10:11] op_sel_hi:[1,0,1]
	v_pk_mul_f32 v[12:13], v[44:45], v[8:9]
	s_nop 0
	v_pk_fma_f32 v[12:13], v[46:47], v[10:11], v[12:13]
	s_nop 0
	v_add_f32_e32 v121, v12, v13
	v_pk_mul_f32 v[12:13], v[52:53], v[8:9]
	v_pk_mul_f32 v[8:9], v[48:49], v[8:9]
	v_pk_fma_f32 v[12:13], v[54:55], v[10:11], v[12:13]
	s_waitcnt lgkmcnt(12)
	v_pk_fma_f32 v[8:9], v[60:61], v[110:111], v[8:9] op_sel_hi:[1,0,1]
	v_add_f32_e32 v12, v12, v13
	v_pk_mul_f32 v[10:11], v[50:51], v[10:11]
	s_nop 0
	v_add_f32_dpp v12, v12, v12 quad_perm:[1,0,3,2] row_mask:0xf bank_mask:0xf bound_ctrl:1
	v_pk_fma_f32 v[10:11], v[62:63], v[110:111], v[10:11] op_sel_hi:[1,0,1]
	s_nop 0
	v_add_f32_dpp v12, v12, v12 quad_perm:[2,3,0,1] row_mask:0xf bank_mask:0xf bound_ctrl:1
	s_nop 1
	v_add_f32_dpp v12, v12, v12 row_half_mirror row_mask:0xf bank_mask:0xf bound_ctrl:1
	s_nop 1
	v_add_f32_dpp v12, v12, v12 row_mirror row_mask:0xf bank_mask:0xf bound_ctrl:1
	v_pk_fma_f32 v[28:29], v[56:57], v[12:13], v[8:9] op_sel_hi:[1,0,1]
	v_pk_fma_f32 v[30:31], v[58:59], v[12:13], v[10:11] op_sel_hi:[1,0,1]
	s_waitcnt lgkmcnt(10)
	v_pk_mul_f32 v[32:33], v[124:125], v[28:29]
	v_pk_mul_f32 v[8:9], v[64:65], v[28:29]
	v_pk_fma_f32 v[32:33], v[126:127], v[30:31], v[32:33]
	v_pk_mul_f32 v[28:29], v[106:107], v[28:29]
	v_add_f32_e32 v32, v32, v33
	v_pk_fma_f32 v[8:9], v[66:67], v[30:31], v[8:9]
	s_waitcnt lgkmcnt(6)
	v_pk_fma_f32 v[28:29], v[132:133], v[170:171], v[28:29] op_sel_hi:[1,0,1]
	v_add_f32_dpp v32, v32, v32 quad_perm:[1,0,3,2] row_mask:0xf bank_mask:0xf bound_ctrl:1
	v_pk_mul_f32 v[30:31], v[108:109], v[30:31]
	v_add_f32_e32 v122, v8, v9
	v_add_f32_dpp v32, v32, v32 quad_perm:[2,3,0,1] row_mask:0xf bank_mask:0xf bound_ctrl:1
	v_pk_fma_f32 v[30:31], v[134:135], v[170:171], v[30:31] op_sel_hi:[1,0,1]
	ds_read_b128 v[16:19], v103 offset:38976
	ds_read_b128 v[24:27], v103 offset:39232
	ds_read_b128 v[12:15], v103 offset:39488
	ds_read_b128 v[20:23], v103 offset:39744
	v_add_f32_dpp v32, v32, v32 row_half_mirror row_mask:0xf bank_mask:0xf bound_ctrl:1
	ds_read_b128 v[8:11], v103 offset:40000
	ds_read_b32 v102, v91 offset:40256
	v_add_f32_dpp v32, v32, v32 row_mirror row_mask:0xf bank_mask:0xf bound_ctrl:1
	v_pk_fma_f32 v[48:49], v[128:129], v[32:33], v[28:29] op_sel_hi:[1,0,1]
	v_pk_fma_f32 v[50:51], v[130:131], v[32:33], v[30:31] op_sel_hi:[1,0,1]
	s_waitcnt lgkmcnt(10)
	v_pk_mul_f32 v[52:53], v[144:145], v[48:49]
	v_pk_mul_f32 v[28:29], v[136:137], v[48:49]
	v_pk_fma_f32 v[52:53], v[146:147], v[50:51], v[52:53]
	v_pk_mul_f32 v[48:49], v[140:141], v[48:49]
	v_add_f32_e32 v52, v52, v53
	v_pk_fma_f32 v[28:29], v[138:139], v[50:51], v[28:29]
	s_waitcnt lgkmcnt(6)
; DEVI float allreduce16(float v) {
;   v = dpp_add<0xB1>(v);
;   v = dpp_add<0x4E>(v);
;   v = dpp_add<0x141>(v);
;   v = dpp_add<0x140>(v);
;   return v;
; }
	v_pk_fma_f32 v[48:49], v[152:153], v[172:173], v[48:49] op_sel_hi:[1,0,1]
	v_add_f32_dpp v52, v52, v52 quad_perm:[1,0,3,2] row_mask:0xf bank_mask:0xf bound_ctrl:1
	v_pk_mul_f32 v[50:51], v[142:143], v[50:51]
	v_add_f32_e32 v123, v28, v29
	v_add_f32_dpp v52, v52, v52 quad_perm:[2,3,0,1] row_mask:0xf bank_mask:0xf bound_ctrl:1
	v_pk_fma_f32 v[50:51], v[154:155], v[172:173], v[50:51] op_sel_hi:[1,0,1]
	ds_read_b128 v[36:39], v103 offset:40320
	ds_read_b128 v[44:47], v103 offset:40576
	ds_read_b128 v[32:35], v103 offset:40832
	ds_read_b128 v[40:43], v103 offset:41088
	v_add_f32_dpp v52, v52, v52 row_half_mirror row_mask:0xf bank_mask:0xf bound_ctrl:1
	ds_read_b128 v[28:31], v103 offset:41344
	ds_read_b32 v104, v91 offset:41600
	v_add_f32_dpp v52, v52, v52 row_mirror row_mask:0xf bank_mask:0xf bound_ctrl:1
	v_pk_fma_f32 v[108:109], v[148:149], v[52:53], v[48:49] op_sel_hi:[1,0,1]
	v_pk_fma_f32 v[106:107], v[150:151], v[52:53], v[50:51] op_sel_hi:[1,0,1]
	s_waitcnt lgkmcnt(10)
	v_pk_mul_f32 v[24:25], v[24:25], v[108:109]
	v_pk_mul_f32 v[16:17], v[16:17], v[108:109]
	v_pk_fma_f32 v[24:25], v[26:27], v[106:107], v[24:25]
	s_waitcnt lgkmcnt(6)
	v_pk_fma_f32 v[16:17], v[20:21], v[102:103], v[16:17] op_sel_hi:[1,0,1]
	v_add_f32_e32 v24, v24, v25
	v_pk_mul_f32 v[18:19], v[18:19], v[106:107]
	v_pk_mul_f32 v[48:49], v[156:157], v[108:109]
	v_add_f32_dpp v20, v24, v24 quad_perm:[1,0,3,2] row_mask:0xf bank_mask:0xf bound_ctrl:1
	v_pk_fma_f32 v[18:19], v[22:23], v[102:103], v[18:19] op_sel_hi:[1,0,1]
	v_pk_fma_f32 v[48:49], v[158:159], v[106:107], v[48:49]
	v_add_f32_dpp v20, v20, v20 quad_perm:[2,3,0,1] row_mask:0xf bank_mask:0xf bound_ctrl:1
	v_add_f32_e32 v124, v48, v49
	ds_read_b128 v[56:59], v103 offset:41664
	v_add_f32_dpp v20, v20, v20 row_half_mirror row_mask:0xf bank_mask:0xf bound_ctrl:1
	ds_read_b128 v[64:67], v103 offset:41920
	ds_read_b128 v[52:55], v103 offset:42176
	v_add_f32_dpp v20, v20, v20 row_mirror row_mask:0xf bank_mask:0xf bound_ctrl:1
	v_pk_fma_f32 v[12:13], v[12:13], v[20:21], v[16:17] op_sel_hi:[1,0,1]
	v_pk_fma_f32 v[14:15], v[14:15], v[20:21], v[18:19] op_sel_hi:[1,0,1]
	v_pk_mul_f32 v[8:9], v[8:9], v[12:13]
	v_cndmask_b32_e64 v18, v115, v122, s[42:43]
	v_pk_fma_f32 v[8:9], v[10:11], v[14:15], v[8:9]
	s_waitcnt lgkmcnt(8)
	v_pk_mul_f32 v[10:11], v[38:39], v[14:15]
	v_add_f32_e32 v16, v8, v9
	s_waitcnt lgkmcnt(7)
	v_pk_mul_f32 v[8:9], v[44:45], v[12:13]
	s_waitcnt lgkmcnt(3)
	v_pk_fma_f32 v[10:11], v[42:43], v[104:105], v[10:11] op_sel_hi:[1,0,1]
	v_pk_fma_f32 v[8:9], v[46:47], v[14:15], v[8:9]
	v_cndmask_b32_e64 v15, v113, v120, s[42:43]
	v_add_f32_e32 v17, v8, v9
	v_pk_mul_f32 v[8:9], v[36:37], v[12:13]
	v_cndmask_b32_e64 v19, v116, v123, s[42:43]
	v_add_f32_dpp v12, v17, v17 quad_perm:[1,0,3,2] row_mask:0xf bank_mask:0xf bound_ctrl:1
	v_pk_fma_f32 v[8:9], v[40:41], v[104:105], v[8:9] op_sel_hi:[1,0,1]
	v_cndmask_b32_e64 v17, v114, v121, s[42:43]
	v_add_f32_dpp v12, v12, v12 quad_perm:[2,3,0,1] row_mask:0xf bank_mask:0xf bound_ctrl:1
	v_cndmask_b32_e64 v20, v117, v124, s[42:43]
	ds_read_b128 v[60:63], v103 offset:42432
	v_add_f32_dpp v12, v12, v12 row_half_mirror row_mask:0xf bank_mask:0xf bound_ctrl:1
	ds_read_b128 v[48:51], v103 offset:42688
	ds_read_b32 v110, v91 offset:42944
	v_add_f32_dpp v12, v12, v12 row_mirror row_mask:0xf bank_mask:0xf bound_ctrl:1
	v_pk_fma_f32 v[8:9], v[32:33], v[12:13], v[8:9] op_sel_hi:[1,0,1]
	v_pk_fma_f32 v[10:11], v[34:35], v[12:13], v[10:11] op_sel_hi:[1,0,1]
	v_pk_mul_f32 v[12:13], v[28:29], v[8:9]
	s_nop 0
	v_pk_fma_f32 v[12:13], v[30:31], v[10:11], v[12:13]
	s_nop 0
	v_add_f32_e32 v14, v12, v13
	s_waitcnt lgkmcnt(4)
	v_pk_mul_f32 v[12:13], v[64:65], v[8:9]
	v_pk_mul_f32 v[8:9], v[56:57], v[8:9]
	v_pk_fma_f32 v[12:13], v[66:67], v[10:11], v[12:13]
	s_waitcnt lgkmcnt(0)
	v_pk_fma_f32 v[8:9], v[60:61], v[110:111], v[8:9] op_sel_hi:[1,0,1]
	v_add_f32_e32 v12, v12, v13
	v_pk_mul_f32 v[10:11], v[58:59], v[10:11]
	s_nop 0
	v_add_f32_dpp v12, v12, v12 quad_perm:[1,0,3,2] row_mask:0xf bank_mask:0xf bound_ctrl:1
	v_pk_fma_f32 v[10:11], v[62:63], v[110:111], v[10:11] op_sel_hi:[1,0,1]
	s_nop 0
	v_add_f32_dpp v12, v12, v12 quad_perm:[2,3,0,1] row_mask:0xf bank_mask:0xf bound_ctrl:1
	s_nop 1
	v_add_f32_dpp v12, v12, v12 row_half_mirror row_mask:0xf bank_mask:0xf bound_ctrl:1
	s_nop 1
	v_add_f32_dpp v12, v12, v12 row_mirror row_mask:0xf bank_mask:0xf bound_ctrl:1
	v_pk_fma_f32 v[8:9], v[52:53], v[12:13], v[8:9] op_sel_hi:[1,0,1]
	v_pk_fma_f32 v[10:11], v[54:55], v[12:13], v[10:11] op_sel_hi:[1,0,1]
	v_pk_mul_f32 v[12:13], v[48:49], v[8:9]
	s_nop 0
	v_pk_fma_f32 v[12:13], v[50:51], v[10:11], v[12:13]
	s_nop 0
	v_add_f32_e32 v12, v12, v13
	v_cndmask_b32_e64 v13, v120, v113, s[42:43]
	s_nop 1
	v_add_f32_dpp v13, v15, v13 row_ror:8 row_mask:0xf bank_mask:0xf bound_ctrl:1
	v_cndmask_b32_e64 v15, v121, v114, s[42:43]
	s_nop 1
	v_add_f32_dpp v15, v17, v15 row_ror:8 row_mask:0xf bank_mask:0xf bound_ctrl:1
	v_cndmask_b32_e64 v17, v122, v115, s[42:43]
	s_nop 1
	v_add_f32_dpp v17, v18, v17 row_ror:8 row_mask:0xf bank_mask:0xf bound_ctrl:1
	v_cndmask_b32_e64 v18, v123, v116, s[42:43]
	s_nop 1
	v_add_f32_dpp v18, v19, v18 row_ror:8 row_mask:0xf bank_mask:0xf bound_ctrl:1
	v_cndmask_b32_e64 v19, v124, v117, s[42:43]
	s_nop 1
	v_add_f32_dpp v19, v20, v19 row_ror:8 row_mask:0xf bank_mask:0xf bound_ctrl:1
	v_cndmask_b32_e64 v20, v16, v111, s[42:43]
	v_cndmask_b32_e64 v16, v111, v16, s[42:43]
	s_nop 1
	v_add_f32_dpp v16, v16, v20 row_ror:8 row_mask:0xf bank_mask:0xf bound_ctrl:1
	v_cndmask_b32_e64 v20, v14, v118, s[42:43]
	v_cndmask_b32_e64 v14, v118, v14, s[42:43]
	s_nop 1
	v_add_f32_dpp v14, v14, v20 row_ror:8 row_mask:0xf bank_mask:0xf bound_ctrl:1
	v_cndmask_b32_e64 v20, v12, v119, s[42:43]
	v_cndmask_b32_e64 v12, v119, v12, s[42:43]
	s_nop 1
	v_add_f32_dpp v12, v12, v20 row_ror:8 row_mask:0xf bank_mask:0xf bound_ctrl:1
	v_cndmask_b32_e64 v20, v19, v13, s[44:45]
	v_cndmask_b32_e64 v13, v13, v19, s[44:45]
	v_cndmask_b32_e64 v19, v16, v15, s[44:45]
	v_cndmask_b32_e64 v15, v15, v16, s[44:45]
	v_cndmask_b32_e64 v16, v14, v17, s[44:45]
	v_cndmask_b32_e64 v14, v17, v14, s[44:45]
	v_add_f32_dpp v13, v13, v20 row_half_mirror row_mask:0xf bank_mask:0xf bound_ctrl:1
	v_add_f32_dpp v15, v15, v19 row_half_mirror row_mask:0xf bank_mask:0xf bound_ctrl:1
	v_add_f32_dpp v14, v14, v16 row_half_mirror row_mask:0xf bank_mask:0xf bound_ctrl:1
	v_cndmask_b32_e64 v16, v12, v18, s[44:45]
	v_cndmask_b32_e64 v12, v18, v12, s[44:45]
	s_nop 1
	v_add_f32_dpp v12, v12, v16 row_half_mirror row_mask:0xf bank_mask:0xf bound_ctrl:1
	v_cndmask_b32_e64 v16, v14, v13, s[46:47]
	v_cndmask_b32_e64 v13, v13, v14, s[46:47]
	v_cndmask_b32_e64 v14, v12, v15, s[46:47]
	v_cndmask_b32_e64 v12, v15, v12, s[46:47]
	v_add_f32_dpp v13, v13, v16 quad_perm:[2,3,0,1] row_mask:0xf bank_mask:0xf bound_ctrl:1
	s_nop 0
	v_add_f32_dpp v12, v12, v14 quad_perm:[2,3,0,1] row_mask:0xf bank_mask:0xf bound_ctrl:1
	v_cndmask_b32_e64 v14, v12, v13, s[48:49]
	v_cndmask_b32_e64 v12, v13, v12, s[48:49]
	s_nop 1
	v_add_f32_dpp v12, v12, v14 quad_perm:[1,0,3,2] row_mask:0xf bank_mask:0xf bound_ctrl:1
	ds_write_b32 v97, v12 offset:44032
	s_cbranch_vccnz .LBB0_194
	v_cvt_f32_f16_e32 v16, v74
	v_cvt_f32_f16_sdwa v17, v74 dst_sel:DWORD dst_unused:UNUSED_PAD src0_sel:WORD_1
	v_cvt_f32_f16_e32 v22, v75
	v_cvt_f32_f16_sdwa v23, v75 dst_sel:DWORD dst_unused:UNUSED_PAD src0_sel:WORD_1
	v_lshlrev_b32_e32 v28, 16, v72
	v_and_b32_e32 v29, 0xffff0000, v72
	v_cvt_f32_f16_sdwa v31, v76 dst_sel:DWORD dst_unused:UNUSED_PAD src0_sel:WORD_1
	v_cvt_f32_f16_e32 v30, v76
	v_pk_mul_f32 v[18:19], v[0:1], v[28:29]
	v_cvt_f32_f16_sdwa v35, v77 dst_sel:DWORD dst_unused:UNUSED_PAD src0_sel:WORD_1
	v_cvt_f32_f16_e32 v34, v77
	v_mul_f32_e32 v16, 0x3fb8aa3b, v16
	v_mul_f32_e32 v17, 0x3fb8aa3b, v17
	v_pk_mul_f32 v[20:21], v[78:79], v[18:19] op_sel_hi:[0,1]
	v_mul_f32_e32 v18, 0x3fb8aa3b, v22
	v_mul_f32_e32 v19, 0x3fb8aa3b, v23
	v_lshlrev_b32_e32 v32, 16, v73
	v_and_b32_e32 v33, 0xffff0000, v73
	v_exp_f32_e32 v16, v16
	v_exp_f32_e32 v17, v17
	v_exp_f32_e32 v18, v18
	v_exp_f32_e32 v19, v19
	v_pk_mul_f32 v[22:23], v[2:3], v[32:33]
	v_pk_mul_f32 v[24:25], v[30:31], v[20:21] neg_lo:[0,1] neg_hi:[0,1]
	v_pk_mul_f32 v[22:23], v[78:79], v[22:23] op_sel_hi:[0,1]
	v_pk_mul_f32 v[26:27], v[34:35], v[22:23] neg_lo:[0,1] neg_hi:[0,1]
	v_pk_add_f32 v[30:31], v[30:31], -1.0 op_sel_hi:[1,0]
	v_pk_add_f32 v[34:35], v[34:35], -1.0 op_sel_hi:[1,0]
	v_pk_fma_f32 v[36:37], v[4:5], v[30:31], 1.0 op_sel_hi:[1,1,0]
	v_pk_fma_f32 v[34:35], v[6:7], v[34:35], 1.0 op_sel_hi:[1,1,0]
	v_lshlrev_b32_e32 v12, 16, v70
	v_and_b32_e32 v13, 0xffff0000, v70
	v_lshlrev_b32_e32 v14, 16, v71
	v_and_b32_e32 v15, 0xffff0000, v71
	v_pk_mul_f32 v[30:31], v[34:35], v[32:33]
	v_pk_mul_f32 v[28:29], v[36:37], v[28:29]
	ds_write_b128 v79, v[16:19]
	ds_write_b128 v79, v[20:23] offset:256
	ds_write_b128 v79, v[24:27] offset:512
	ds_write_b128 v79, v[28:31] offset:768
	ds_write_b128 v79, v[12:15] offset:1024
	s_and_saveexec_b64 s[50:51], s[40:41]
	s_cbranch_execz .LBB0_193
	v_lshlrev_b32_e32 v12, 16, v68
	v_and_b32_e32 v13, 0xffff0000, v68
	v_lshlrev_b32_e32 v14, 16, v69
	v_and_b32_e32 v15, 0xffff0000, v69
	ds_write_b128 v79, v[12:15] offset:1280
	s_branch .LBB0_193
	s_nop 0
	s_nop 0
	s_nop 0
	s_nop 0
	s_nop 0
	s_nop 0
